# scan stages 1 and 3 with swapped MFMA operands: attention tile and state image written with ds_write_b64 instead of 24 ds_write_b16, half the converts
# speedup vs baseline: 1.0041x; 1.0004x over previous
.LBB0_574:
	s_and_b64 vcc, exec, s[12:13]
	s_cbranch_vccz .LBB0_556
	v_and_b32_e32 v107, 15, v113
	v_and_b32_e32 v133, 48, v113
	v_or_b32_e32 v132, s72, v107
	v_add_u32_e32 v20, 0, v133
	v_mad_u64_u32 v[22:23], s[12:13], v132, s53, v[20:21]
	v_lshrrev_b32_e32 v60, 4, v111
	v_lshlrev_b32_e32 v109, 2, v60
	v_or_b32_e32 v61, s77, v107
	v_or_b32_e32 v62, s78, v107
	v_add_u32_e32 v151, s77, v109
	v_add_u32_e32 v152, s78, v109
	s_and_b64 vcc, exec, s[8:9]
	s_cbranch_vccnz .Ls1_noacum
	v_lshl_add_u32 v150, v132, 2, s71
	v_lshl_add_u32 v153, v151, 2, s71
	v_lshl_add_u32 v128, v152, 2, s71
	ds_read_b32 v166, v150 offset:256
	ds_read_b128 v[168:171], v153 offset:256
	ds_read_b128 v[172:175], v128 offset:256
.Ls1_noacum:
	ds_read_b128 v[16:19], v22
	ds_read_b128 v[80:83], v22 offset:64
	ds_read_b128 v[84:87], v22 offset:128
	ds_read_b128 v[96:99], v22 offset:192
	s_andn2_b64 vcc, exec, s[46:47]
	s_cbranch_vccnz .Ls1_none
	v_mad_u32_u24 v23, v61, s53, v20
	ds_read_b128 v[154:157], v23 offset:17408
	ds_read_b128 v[158:161], v23 offset:17472
	ds_read_b128 v[162:165], v23 offset:17536
	ds_read_b128 v[176:179], v23 offset:17600
	s_andn2_b64 vcc, exec, s[48:49]
	s_cbranch_vccnz .Ls1_only0
	v_mad_u32_u24 v129, v62, s53, v20
	ds_read_b128 v[68:71], v129 offset:17408
	ds_read_b128 v[72:75], v129 offset:17472
	ds_read_b128 v[76:79], v129 offset:17536
	ds_read_b128 v[100:103], v129 offset:17600
	s_waitcnt lgkmcnt(7)
	v_mfma_f32_16x16x32_bf16 v[56:59], v[154:157], v[16:19], 0
	s_waitcnt lgkmcnt(3)
	v_mfma_f32_16x16x32_bf16 v[64:67], v[68:71], v[16:19], 0
	v_mfma_f32_16x16x32_bf16 v[56:59], v[158:161], v[80:83], v[56:59]
	s_waitcnt lgkmcnt(2)
	v_mfma_f32_16x16x32_bf16 v[64:67], v[72:75], v[80:83], v[64:67]
	v_mfma_f32_16x16x32_bf16 v[56:59], v[162:165], v[84:87], v[56:59]
	s_waitcnt lgkmcnt(1)
	v_mfma_f32_16x16x32_bf16 v[64:67], v[76:79], v[84:87], v[64:67]
	v_mfma_f32_16x16x32_bf16 v[56:59], v[176:179], v[96:99], v[56:59]
	s_waitcnt lgkmcnt(0)
	v_mfma_f32_16x16x32_bf16 v[64:67], v[100:103], v[96:99], v[64:67]
	s_branch .Ls1_mdone
.Ls1_only0:
	v_mov_b32_e32 v64, 0
	v_mov_b32_e32 v65, 0
	v_mov_b32_e32 v66, 0
	v_mov_b32_e32 v67, 0
	s_waitcnt lgkmcnt(3)
	v_mfma_f32_16x16x32_bf16 v[56:59], v[154:157], v[16:19], 0
	s_waitcnt lgkmcnt(2)
	v_mfma_f32_16x16x32_bf16 v[56:59], v[158:161], v[80:83], v[56:59]
	s_waitcnt lgkmcnt(1)
	v_mfma_f32_16x16x32_bf16 v[56:59], v[162:165], v[84:87], v[56:59]
	s_waitcnt lgkmcnt(0)
	v_mfma_f32_16x16x32_bf16 v[56:59], v[176:179], v[96:99], v[56:59]
	s_branch .Ls1_mdone

.Ls1_mdone:
	v_add_u32_e32 v131, -1, v132
	v_add_u32_e32 v127, -2, v132
	v_add_u32_e32 v23, -3, v132
	v_cmp_le_i32_e64 s[12:13], v151, v132
	v_cmp_le_i32_e64 s[88:89], v151, v131
	v_cmp_le_i32_e64 s[90:91], v151, v127
	v_cmp_le_i32_e64 s[92:93], v151, v23
	v_cmp_le_i32_e64 s[94:95], v152, v132
	v_cmp_le_i32_e64 s[96:97], v152, v131
	v_cmp_le_i32_e64 s[98:99], v152, v127
	v_cmp_le_i32_e64 s[100:101], v152, v23
	v_mul_u32_u24_e32 v150, s54, v132
	v_lshl_add_u32 v153, v151, 1, v150
	v_lshl_add_u32 v128, v152, 1, v150
	v_cndmask_b32_e64 v56, 0, v56, s[12:13]
	v_cndmask_b32_e64 v57, 0, v57, s[88:89]
	v_cndmask_b32_e64 v58, 0, v58, s[90:91]
	v_cndmask_b32_e64 v59, 0, v59, s[92:93]
	v_cndmask_b32_e64 v64, 0, v64, s[94:95]
	v_cndmask_b32_e64 v65, 0, v65, s[96:97]
	v_cndmask_b32_e64 v66, 0, v66, s[98:99]
	v_cndmask_b32_e64 v67, 0, v67, s[100:101]
	s_and_b64 vcc, exec, s[8:9]
	s_cbranch_vccnz .Ls1_write
	s_waitcnt lgkmcnt(0)
	v_sub_f32_e32 v180, v166, v168
	v_sub_f32_e32 v181, v166, v169
	v_sub_f32_e32 v182, v166, v170
	v_sub_f32_e32 v183, v166, v171
	v_sub_f32_e32 v184, v166, v172
	v_sub_f32_e32 v185, v166, v173
	v_sub_f32_e32 v186, v166, v174
	v_sub_f32_e32 v187, v166, v175
	v_min_f32_e32 v180, 0, v180
	v_min_f32_e32 v181, 0, v181
	v_min_f32_e32 v182, 0, v182
	v_min_f32_e32 v183, 0, v183
	v_min_f32_e32 v184, 0, v184
	v_min_f32_e32 v185, 0, v185
	v_min_f32_e32 v186, 0, v186
	v_min_f32_e32 v187, 0, v187
	v_mul_f32_e32 v180, 0x3fb8aa3b, v180
	v_mul_f32_e32 v181, 0x3fb8aa3b, v181
	v_mul_f32_e32 v182, 0x3fb8aa3b, v182
	v_mul_f32_e32 v183, 0x3fb8aa3b, v183
	v_mul_f32_e32 v184, 0x3fb8aa3b, v184
	v_mul_f32_e32 v185, 0x3fb8aa3b, v185
	v_mul_f32_e32 v186, 0x3fb8aa3b, v186
	v_mul_f32_e32 v187, 0x3fb8aa3b, v187
	v_exp_f32_e32 v180, v180
	v_exp_f32_e32 v181, v181
	v_exp_f32_e32 v182, v182
	v_exp_f32_e32 v183, v183
	v_exp_f32_e32 v184, v184
	v_exp_f32_e32 v185, v185
	v_exp_f32_e32 v186, v186
	v_exp_f32_e32 v187, v187
	v_mul_f32_e32 v56, v56, v180
	v_mul_f32_e32 v57, v57, v181
	v_mul_f32_e32 v58, v58, v182
	v_mul_f32_e32 v59, v59, v183
	v_mul_f32_e32 v64, v64, v184
	v_mul_f32_e32 v65, v65, v185
	v_mul_f32_e32 v66, v66, v186
	v_mul_f32_e32 v67, v67, v187
.Ls1_write:
	v_cvt_pk_bf16_f32 v56, v56, v57
	v_cvt_pk_bf16_f32 v57, v58, v59
	v_cvt_pk_bf16_f32 v64, v64, v65
	v_cvt_pk_bf16_f32 v65, v66, v67
	ds_write_b64 v153, v[56:57] offset:61440
	ds_write_b64 v128, v[64:65] offset:61440
	v_lshrrev_b32_e32 v57, 2, v107
	v_lshlrev_b32_e32 v20, 3, v113
	v_lshl_or_b32 v60, v60, 3, v57
	v_lshl_add_u32 v56, v107, 2, s73
	s_waitcnt lgkmcnt(4)
	v_and_b32_e32 v61, 24, v20
	v_mul_u32_u24_e32 v57, 0x110, v60
	v_add3_u32 v114, s81, v61, v57
	ds_read_b32 v56, v56
	v_mad_u32_u24 v130, v60, s54, v61
	v_add_u32_e32 v115, s66, v130
	ds_read_b64_tr_b16 v[146:147], v114 offset:0
	ds_read_b64_tr_b16 v[148:149], v114 offset:1088
	ds_read_b64_tr_b16 v[142:143], v114 offset:8704
	ds_read_b64_tr_b16 v[144:145], v114 offset:9792
	ds_read_b64_tr_b16 v[138:139], v115 offset:0
	ds_read_b64_tr_b16 v[140:141], v115 offset:576
	ds_read_b64_tr_b16 v[134:135], v115 offset:4608
	ds_read_b64_tr_b16 v[136:137], v115 offset:5184
	ds_read_b64_tr_b16 v[100:101], v115 offset:32
	ds_read_b64_tr_b16 v[102:103], v115 offset:608
	ds_read_b64_tr_b16 v[76:77], v115 offset:4640
	ds_read_b64_tr_b16 v[78:79], v115 offset:5216
	ds_read_b64_tr_b16 v[72:73], v115 offset:64
	ds_read_b64_tr_b16 v[74:75], v115 offset:640
	ds_read_b64_tr_b16 v[68:69], v115 offset:4672
	ds_read_b64_tr_b16 v[70:71], v115 offset:5248
	ds_read_b64_tr_b16 v[64:65], v115 offset:96
	ds_read_b64_tr_b16 v[66:67], v115 offset:672
	ds_read_b64_tr_b16 v[60:61], v115 offset:4704
	ds_read_b64_tr_b16 v[62:63], v115 offset:5280
	s_waitcnt lgkmcnt(0)
	s_cmp_eq_u32 s83, 63
	s_waitcnt lgkmcnt(0)
	v_pk_mul_f32 v[2:3], v[2:3], v[56:57] op_sel_hi:[1,0]
	v_pk_mul_f32 v[0:1], v[0:1], v[56:57] op_sel_hi:[1,0]
	v_pk_mul_f32 v[6:7], v[6:7], v[56:57] op_sel_hi:[1,0]
	v_pk_mul_f32 v[4:5], v[4:5], v[56:57] op_sel_hi:[1,0]
	v_pk_mul_f32 v[10:11], v[10:11], v[56:57] op_sel_hi:[1,0]
	v_pk_mul_f32 v[8:9], v[8:9], v[56:57] op_sel_hi:[1,0]
	v_pk_mul_f32 v[14:15], v[14:15], v[56:57] op_sel_hi:[1,0]
	v_pk_mul_f32 v[12:13], v[12:13], v[56:57] op_sel_hi:[1,0]
	v_mfma_f32_16x16x32_bf16 v[0:3], v[138:141], v[146:149], v[0:3]
	v_mfma_f32_16x16x32_bf16 v[4:7], v[100:103], v[146:149], v[4:7]
	v_mfma_f32_16x16x32_bf16 v[8:11], v[72:75], v[146:149], v[8:11]
	v_mfma_f32_16x16x32_bf16 v[12:15], v[64:67], v[146:149], v[12:15]
	v_mfma_f32_16x16x32_bf16 v[0:3], v[134:137], v[142:145], v[0:3]
	v_mfma_f32_16x16x32_bf16 v[4:7], v[76:79], v[142:145], v[4:7]
	v_mfma_f32_16x16x32_bf16 v[8:11], v[68:71], v[142:145], v[8:11]
	v_mfma_f32_16x16x32_bf16 v[12:15], v[60:63], v[142:145], v[12:15]
	s_cbranch_scc1 .LBB0_605
	s_add_i32 s50, s69, 64
	v_and_b32_e32 v24, 0x78, v20
	v_ashrrev_i32_e32 v25, 4, v113
	v_add_u32_e32 v26, 0x200, v113
	v_ashrrev_i32_e32 v27, 3, v113
	v_and_b32_e32 v28, 56, v20
	s_mov_b64 s[12:13], -1
	s_and_b64 vcc, exec, s[10:11]
	v_lshlrev_b32_e32 v20, 1, v24
	v_add_u32_e32 v24, s50, v25
	v_ashrrev_i32_e32 v32, 4, v26
	v_add_u32_e32 v26, s50, v27
	v_lshlrev_b32_e32 v114, 1, v28
	s_cbranch_vccnz .LBB0_602
	v_mov_b32_e32 v56, v24
	v_mov_b32_e32 v58, v26
	v_add_u32_e32 v62, s50, v32
	v_lshl_add_u64 v[60:61], s[36:37], 0, v[20:21]
	v_ashrrev_i32_e32 v57, 31, v56
	v_mad_i64_i32 v[64:65], s[12:13], v56, s3, v[60:61]
	v_lshl_add_u64 v[66:67], s[38:39], 0, v[20:21]
	global_load_dwordx4 v[24:27], v[64:65], off
	global_load_dwordx4 v[32:35], v[64:65], off offset:1024
	v_lshlrev_b64 v[64:65], 10, v[56:57]
	v_lshl_add_u64 v[64:65], v[66:67], 0, v[64:65]
	global_load_dwordx4 v[40:43], v[64:65], off
	v_ashrrev_i32_e32 v63, 31, v62
	v_mad_i64_i32 v[60:61], s[12:13], v62, s3, v[60:61]
	global_load_dwordx4 v[28:31], v[60:61], off
	global_load_dwordx4 v[36:39], v[60:61], off offset:1024
	v_lshlrev_b64 v[60:61], 10, v[62:63]
	v_lshl_add_u64 v[60:61], v[66:67], 0, v[60:61]
	global_load_dwordx4 v[44:47], v[60:61], off
	v_mov_b64_e32 v[60:61], s[40:41]
	v_mad_i64_i32 v[60:61], s[12:13], v58, s3, v[60:61]
	v_mov_b32_e32 v115, v21
	v_lshl_add_u64 v[60:61], v[60:61], 0, v[114:115]
	global_load_dwordx4 v[92:95], v[60:61], off
	v_cmp_gt_i32_e32 vcc, 32, v113
	s_and_saveexec_b64 s[12:13], vcc
	s_cbranch_execz .LBB0_601
	s_add_i32 s86, s82, s83
	s_ashr_i32 s87, s86, 31
	s_lshl_b64 s[86:87], s[86:87], 11
	s_add_u32 s86, s74, s86
	v_lshlrev_b32_e32 v60, 2, v113
	s_addc_u32 s87, s75, s87
	v_ashrrev_i32_e32 v61, 31, v60
	v_lshl_add_u64 v[60:61], v[60:61], 2, s[86:87]
	global_load_dwordx4 v[88:91], v[60:61], off

.LBB0_687:
	v_or_b32_e32 v16, s76, v107
	v_lshlrev_b32_e32 v17, 1, v109
	v_mul_lo_u32 v16, v16, s54
	v_add3_u32 v16, s67, v17, v16
	v_cvt_pk_bf16_f32 v18, v0, v1
	v_cvt_pk_bf16_f32 v19, v2, v3
	v_cvt_pk_bf16_f32 v22, v4, v5
	v_cvt_pk_bf16_f32 v23, v6, v7
	s_barrier
	ds_write_b64 v16, v[18:19]
	ds_write_b64 v16, v[22:23] offset:32
	v_cvt_pk_bf16_f32 v18, v8, v9
	v_cvt_pk_bf16_f32 v19, v10, v11
	v_cvt_pk_bf16_f32 v22, v12, v13
	v_cvt_pk_bf16_f32 v23, v14, v15
	ds_write_b64 v16, v[18:19] offset:64
	ds_write_b64 v16, v[22:23] offset:96
	s_add_i32 s69, s69, 64
	s_addk_i32 s71, 0x200
	s_add_i32 s83, s83, 1
	s_cmp_lg_u32 s83, 64
	s_cbranch_scc1 .LBB0_557
	s_branch .LBB0_534
